# attention steady loops (GQA + differential): shorter row-max tree, no x+0, LDS-DMA source addresses via SGPR base + lane offset
# speedup vs baseline: 1.0099x; 1.0006x over previous
;   #define WB(a,b) do{ if constexpr(DV2){WAIT_BAR(b);} else {WAIT_BAR(a);} }while(0)
;   #define DMA_K(t,slot) glds16(ksrc+(long)TMAP(t)*KVBLK*PQ,(unsigned)__builtin_amdgcn_readfirstlane(kdst+(slot)))
;   #define DMA_V(t,slot) glds16(vsrc+(long)TMAP(t)*KVBLK*PQ,(unsigned)__builtin_amdgcn_readfirstlane(vdst+(slot)))
;   #define DMA_V2(t,slot) do{ if constexpr(DV2) glds16(v2src+(long)TMAP(t)*KVBLK*PQ,(unsigned)__builtin_amdgcn_readfirstlane(v2dst+(slot))); }while(0)
;     ...
;   int tid=threadIdx.x; asm volatile("":"+v"(tid)); const int lane=tid&63,r32=lane&31,hi=lane>>5; const int wid=__builtin_amdgcn_readfirstlane(tid>>6);
;   const bf16*Qw=Qu+(long)wid*QBLK*PQ;
;   const unsigned lds0=(unsigned)(uintptr_t)shm;
;   float*wsf=(float*)(shm+LDS_WS)+wid*64;
;   const bf16*ksrc=Kh+(long)lane*PQ+wid*8;
;   const bf16*vsrc=Vh+(long)(16*(wid&3)+(lane>>2))*PQ+(wid>>2)*32+(lane&3)*8;
;   const unsigned kdst=lds0+LDS_K+wid*1024, vdst=lds0+LDS_V+wid*1024;
;     ...
;   const bf16*v2src=DV2?V2h+(vsrc-Vh):vsrc; const unsigned v2dst=lds0+LDS_V2+wid*1024;
;     ...
;   const int vb0=(int)(lds0+LDS_V)+((lane>>4)&1)*32+(lane&3)*8+(4*hi+((lane&15)>>2))*64;
;   const char*Kbase=shm+LDS_K; bf16x8 kf[8];
;   const lds_cptr shm3=(lds_cptr)shm; const lds_cptr kp0=shm3+LDS_K+hi*1024+r32*16; const lds_cptr vp0=shm3+LDS_V+((lane>>4)&1)*32+(lane&3)*8+(4*hi+((lane&15)>>2))*64;
;   DMA_K(0,0);DMA_V(0,0);DMA_V2(0,0);DMA_K(1,SLOTB);
;   bf16x8 qr[4];
;   #pragma unroll
;   for(int d0=0;d0<4;++d0)qr[d0]=*reinterpret_cast<const bf16x8*>(&Qw[(long)r32*PQ+d0*16+hi*8]);
;   float mhat=0.f,l_reg=0.f;f32x16 o[ND];
;   #pragma unroll
;   for(int d_=0;d_<ND;++d_)o[d_]=f32x16{};
;   f32x16 negm=f32x16{}; if constexpr(!DV2) asm volatile("":"+v"(negm));
;   const f32x16 zero16=f32x16{};
;     ...
;   const int nq_r=qrow0+(wid>>1), nq_c=(wid&1)*32+r32, n_rsw=min(max(nq_r-4,0),56), n_cs=min(max(nq_c-8,0),48);
;     ...
;   bool resc=false;
;     ...
;   f32x16 pA0,pA1,pB0,pB1;
;   int sl_prev=0,sl_cur=0,sl_next=SLOTB;
;     ...
;   DMA_K(2,2*SLOTB);
;   WB(3,4);
;   qkt(pA0,pA1,Kbase,qr,NEGM,r32,hi);asm volatile("s_nop 15\n\ts_nop 7":"+v"(pA0),"+v"(pA1));CMASK(pA0,pA1,0);
.LBB0_258:
	s_or_b32 s13, s42, s40
	s_mul_i32 s6, s13, 0x1100
	s_mul_hi_u32 s7, s13, 0x1100
	s_add_u32 s6, s6, s38
	s_addc_u32 s7, s7, 0
	s_lshl_b64 s[6:7], s[6:7], 7
	v_readlane_b32 s44, v254, 25
	v_readlane_b32 s45, v254, 26
	s_add_u32 s16, s44, s6
	v_readlane_b32 s46, v254, 27
	s_addc_u32 s17, s45, s7
	s_mul_hi_u32 s6, s13, 0x88000
	s_mul_i32 s13, s13, 0x88000
	v_mov_b32_e32 v14, v234
	v_readlane_b32 s47, v254, 28
	s_add_u32 s14, s46, s13
	s_addc_u32 s15, s47, s6
	v_readfirstlane_b32 s13, v14
	s_ashr_i32 s30, s13, 6
	s_ashr_i32 s31, s30, 31
	v_and_b32_e32 v243, 63, v14
	s_lshl_b64 s[6:7], s[30:31], 12
	s_add_u32 s16, s16, s6
	v_lshlrev_b32_e32 v0, 7, v243
	s_addc_u32 s17, s17, s7
	v_lshl_add_u64 v[2:3], s[14:15], 0, v[0:1]
	s_lshl_b32 s14, s30, 3
	s_lshl_b32 s7, s30, 4
	v_bfe_u32 v0, v14, 2, 4
	s_ashr_i32 s15, s14, 31
	v_and_or_b32 v0, s7, 48, v0
	s_ashr_i32 s7, s13, 3
	v_lshl_add_u64 v[224:225], s[14:15], 1, v[2:3]
	s_and_b32 s14, s7, 0xffffffe0
	s_ashr_i32 s15, s14, 31
	s_and_b32 s6, s13, 0x3fffffc0
	v_lshlrev_b32_e32 v0, 7, v0
	s_lshl_b64 s[14:15], s[14:15], 1
	v_lshlrev_b32_e32 v4, 3, v14
	s_lshl_b32 s43, s30, 10
	v_lshl_add_u64 v[2:3], s[10:11], 0, v[0:1]
	v_and_b32_e32 v244, 24, v4
	s_cmp_lg_u32 0, -1
	v_lshl_add_u64 v[2:3], v[2:3], 0, s[14:15]
	v_lshlrev_b32_e32 v4, 1, v244
	v_mov_b32_e32 v5, v1
	s_cselect_b32 s7, 0, 0
	v_lshl_add_u64 v[226:227], v[2:3], 0, v[4:5]
	s_add_i32 s43, s43, s7
	v_lshl_add_u64 v[2:3], s[28:29], 0, v[0:1]
	s_mov_b32 s7, m0
	s_mov_b32 m0, s43
	s_nop 0
	global_load_lds_dwordx4 v[224:225], off
	s_mov_b32 m0, s7
	v_and_b32_e32 v211, 31, v14
	s_add_i32 s44, s43, 0x6000
	v_lshl_add_u64 v[2:3], v[2:3], 0, s[14:15]
	s_mov_b32 s7, m0
	s_mov_b32 m0, s44
	s_nop 0
	global_load_lds_dwordx4 v[226:227], off
	s_mov_b32 m0, s7
	v_bfe_u32 v242, v14, 5, 1
	v_lshl_add_u64 v[228:229], v[2:3], 0, v[4:5]
	s_add_i32 s45, s43, 0x14800
	s_mov_b32 s7, m0
	s_mov_b32 m0, s45
	s_nop 0
	global_load_lds_dwordx4 v[228:229], off
	s_mov_b32 m0, s7
	v_lshlrev_b32_e32 v0, 7, v211
	v_lshl_add_u64 v[2:3], v[224:225], 0, s[86:87]
	s_add_i32 s7, s43, 0x2000
	s_mov_b32 s13, m0
	s_mov_b32 m0, s7
	s_nop 0
	global_load_lds_dwordx4 v[2:3], off
	s_mov_b32 m0, s13
	v_lshl_or_b32 v0, v242, 4, v0
	global_load_dwordx4 v[162:165], v0, s[16:17]
	global_load_dwordx4 v[158:161], v0, s[16:17] offset:32
	global_load_dwordx4 v[154:157], v0, s[16:17] offset:64
	global_load_dwordx4 v[146:149], v0, s[16:17] offset:96
	v_lshlrev_b32_e32 v0, 10, v242
	v_lshlrev_b32_e32 v2, 4, v211
	v_add3_u32 v250, 0, v0, v2
	v_lshl_add_u64 v[2:3], v[224:225], 0, s[96:97]
	s_add_i32 s7, s43, 0x4000
	s_mov_b32 s13, m0
	s_mov_b32 m0, s7
	s_nop 0
	global_load_lds_dwordx4 v[2:3], off
	s_mov_b32 m0, s13
	s_waitcnt vmcnt(4) lgkmcnt(0)
	s_barrier
	ds_read_b128 v[2:5], v250
	ds_read_b128 v[6:9], v250 offset:512
	v_lshlrev_b32_e32 v0, 1, v14
	v_and_b32_e32 v247, 32, v0
	s_lshl_b32 s6, s6, 2
	s_add_i32 s33, s6, 0
	s_mov_b32 s82, 1
	s_movk_i32 s47, 0x2000
	s_movk_i32 s46, 0x4000
	s_andn2_b64 vcc, exec, s[4:5]
	v_lshlrev_b32_e32 v252, 4, v242
	v_lshl_add_u32 v245, v211, 2, s33
	v_readlane_b32 s48, v254, 29
	v_readlane_b32 s49, v254, 30
	v_readlane_b32 s50, v254, 31
	v_readlane_b32 s51, v254, 32
	v_readlane_b32 s52, v254, 33
	v_readlane_b32 s53, v254, 34
	v_readlane_b32 s54, v254, 35
	v_readlane_b32 s55, v254, 36
	v_readlane_b32 s56, v254, 37
	v_readlane_b32 s57, v254, 38
	v_readlane_b32 s58, v254, 39
	v_readlane_b32 s59, v254, 40
	s_waitcnt vmcnt(3) lgkmcnt(1)
	v_mfma_f32_32x32x16_bf16 v[34:49], v[2:5], v[162:165], 0
	s_waitcnt lgkmcnt(0)
	v_mfma_f32_32x32x16_bf16 v[18:33], v[6:9], v[162:165], 0
	ds_read_b128 v[2:5], v250 offset:2048
	ds_read_b128 v[6:9], v250 offset:2560
	s_waitcnt vmcnt(2) lgkmcnt(1)
	v_mfma_f32_32x32x16_bf16 v[34:49], v[2:5], v[158:161], v[34:49]
	ds_read_b128 v[2:5], v250 offset:4096
	s_waitcnt lgkmcnt(1)
	v_mfma_f32_32x32x16_bf16 v[18:33], v[6:9], v[158:161], v[18:33]
	ds_read_b128 v[6:9], v250 offset:4608
	s_waitcnt vmcnt(1) lgkmcnt(1)
	v_mfma_f32_32x32x16_bf16 v[34:49], v[2:5], v[154:157], v[34:49]
	ds_read_b128 v[2:5], v250 offset:6656
	ds_read_b128 v[10:13], v250 offset:6144
	s_waitcnt lgkmcnt(2)
	v_mfma_f32_32x32x16_bf16 v[18:33], v[6:9], v[154:157], v[18:33]
	v_lshlrev_b32_e32 v6, 4, v14
	v_and_b32_e32 v0, 0xc0, v6
	v_lshl_or_b32 v246, v242, 8, v0
	v_add_u32_e32 v0, 0, v247
	v_add3_u32 v251, v0, v244, v246
	v_add_u32_e32 v249, 0x6000, v251
	s_waitcnt vmcnt(0) lgkmcnt(0)
	v_mfma_f32_32x32x16_bf16 v[34:49], v[10:13], v[146:149], v[34:49]
	v_mfma_f32_32x32x16_bf16 v[18:33], v[2:5], v[146:149], v[18:33]
	s_nop 15
	s_nop 7
	s_waitcnt vmcnt(0) lgkmcnt(0)
	s_barrier
; #define WAIT_BAR(N) asm volatile("s_waitcnt vmcnt(" #N ") lgkmcnt(0)\n\ts_barrier":::"memory")
;   #define WB(a,b) do{ if constexpr(DV2){WAIT_BAR(b);} else {WAIT_BAR(a);} }while(0)
;   #define DMA_K(t,slot) glds16(ksrc+(long)TMAP(t)*KVBLK*PQ,(unsigned)__builtin_amdgcn_readfirstlane(kdst+(slot)))
;   #define DMA_V(t,slot) glds16(vsrc+(long)TMAP(t)*KVBLK*PQ,(unsigned)__builtin_amdgcn_readfirstlane(vdst+(slot)))
;   #define DMA_V2(t,slot) do{ if constexpr(DV2) glds16(v2src+(long)TMAP(t)*KVBLK*PQ,(unsigned)__builtin_amdgcn_readfirstlane(v2dst+(slot))); }while(0)
;   #define ROT() do{sl_prev=sl_cur;sl_cur=sl_next;sl_next=(sl_next==(NSLOT-1)*SLOTB)?0:sl_next+SLOTB;}while(0)
;     ...
;   f32x16 pA0,pA1,pB0,pB1;
;   int sl_prev=0,sl_cur=0,sl_next=SLOTB;
;     ...
;   DMA_K(2,2*SLOTB);
;   WB(3,4);
;   qkt(pA0,pA1,Kbase,qr,NEGM,r32,hi);asm volatile("s_nop 15\n\ts_nop 7":"+v"(pA0),"+v"(pA1));CMASK(pA0,pA1,0);
;   START(pA0,pA1);
;   _Pragma("unroll") for(int r=0;r<16;++r)pA1[r]=__builtin_amdgcn_exp2f(pA1[r]);
;   WAIT_BAR(0);
;   DMA_K(3,0);DMA_V(1,SLOTB);DMA_V2(1,SLOTB);
;   ROT();
;   kload8(kf,kp0+sl_cur);
;   WB(2,3);
;   s16x4 vlo[8],vhi[8]; u32x4 pw0,pw1,pw2,pw3;
	s_nop 0
	v_max3_f32 v2, v34, v35, v18
	v_max3_f32 v3, v36, v37, v19
	s_nop 0
	v_max3_f32 v2, v2, v20, v21
	v_max3_f32 v3, v3, v40, v41
	s_nop 0
	v_max3_f32 v2, v2, v38, v39
	v_max3_f32 v3, v3, v24, v25
	s_nop 0
	v_max3_f32 v2, v2, v22, v23
	v_max3_f32 v3, v3, v44, v45
	s_nop 0
	v_max3_f32 v2, v2, v42, v43
	v_max3_f32 v3, v3, v28, v29
	s_nop 0
	v_max3_f32 v2, v2, v26, v27
	v_max3_f32 v3, v3, v48, v49
	s_nop 0
	v_max3_f32 v2, v2, v46, v47
	v_max3_f32 v3, v3, v32, v33
	s_nop 0
	v_max3_f32 v2, v2, v30, v31
	s_nop 0
	v_max_f32_e32 v2, v2, v3
	s_nop 0
	v_mov_b32_e32 v3, v2
	s_nop 1
	v_permlane32_swap_b32_e32 v2, v3
	v_max_f32_e32 v2, v2, v3
	s_nop 0
	v_add_f32_e32 v248, v1, v2
	v_sub_f32_e32 v3, v34, v2
	v_sub_f32_e32 v4, v18, v2
	v_sub_f32_e32 v5, v35, v2
	v_sub_f32_e32 v6, v19, v2
	v_sub_f32_e32 v7, v36, v2
	v_sub_f32_e32 v8, v20, v2
	v_sub_f32_e32 v9, v37, v2
	v_sub_f32_e32 v10, v21, v2
	v_sub_f32_e32 v11, v38, v2
	v_sub_f32_e32 v12, v22, v2
	v_sub_f32_e32 v13, v39, v2
	v_sub_f32_e32 v14, v23, v2
	v_sub_f32_e32 v15, v40, v2
	v_sub_f32_e32 v18, v24, v2
	v_sub_f32_e32 v19, v41, v2
	v_sub_f32_e32 v20, v25, v2
	v_sub_f32_e32 v21, v42, v2
	v_sub_f32_e32 v22, v26, v2
	v_sub_f32_e32 v23, v43, v2
	v_sub_f32_e32 v24, v27, v2
	v_sub_f32_e32 v25, v44, v2
	v_sub_f32_e32 v26, v28, v2
	v_sub_f32_e32 v27, v45, v2
	v_sub_f32_e32 v28, v29, v2
	v_sub_f32_e32 v29, v46, v2
	v_sub_f32_e32 v30, v30, v2
	v_sub_f32_e32 v34, v47, v2
	v_sub_f32_e32 v31, v31, v2
	v_sub_f32_e32 v35, v48, v2
	v_sub_f32_e32 v32, v32, v2
	v_sub_f32_e32 v36, v49, v2
	v_sub_f32_e32 v2, v33, v2
	s_nop 0
	v_exp_f32_e32 v98, v3
	v_exp_f32_e32 v97, v2
	v_lshl_add_u64 v[2:3], v[224:225], 0, s[0:1]
	s_mov_b32 s6, m0
	s_mov_b32 m0, s43
	s_nop 0
	global_load_lds_dwordx4 v[2:3], off
	s_mov_b32 m0, s6
	v_lshl_add_u64 v[2:3], v[226:227], 0, s[86:87]
	s_add_i32 s6, s43, 0x8000
	s_mov_b32 s7, m0
	s_mov_b32 m0, s6
	s_nop 0
	global_load_lds_dwordx4 v[2:3], off
	s_mov_b32 m0, s7
	v_lshl_add_u64 v[2:3], v[228:229], 0, s[86:87]
	s_add_i32 s6, s43, 0x16800
	s_mov_b32 s7, m0
	s_mov_b32 m0, s6
	s_nop 0
	global_load_lds_dwordx4 v[2:3], off
	s_mov_b32 m0, s7
	ds_read_b128 v[194:197], v250 offset:8192
	ds_read_b128 v[186:189], v250 offset:8704
	ds_read_b128 v[190:193], v250 offset:10240
	ds_read_b128 v[182:185], v250 offset:10752
	ds_read_b128 v[178:181], v250 offset:12288
	ds_read_b128 v[174:177], v250 offset:12800
	ds_read_b128 v[170:173], v250 offset:14336
	ds_read_b128 v[166:169], v250 offset:14848
	v_exp_f32_e32 v99, v5
	v_exp_f32_e32 v100, v7
	v_exp_f32_e32 v101, v9
	v_exp_f32_e32 v102, v11
	v_exp_f32_e32 v103, v13
	v_exp_f32_e32 v104, v15
	v_exp_f32_e32 v105, v19
	v_exp_f32_e32 v106, v21
	v_exp_f32_e32 v107, v23
	v_exp_f32_e32 v108, v25
	v_exp_f32_e32 v109, v27
	v_exp_f32_e32 v110, v29
	v_exp_f32_e32 v111, v34
	v_exp_f32_e32 v112, v35
	v_exp_f32_e32 v113, v36
	v_exp_f32_e32 v82, v4
	v_exp_f32_e32 v83, v6
	v_exp_f32_e32 v84, v8
	v_exp_f32_e32 v85, v10
	v_exp_f32_e32 v86, v12
	v_exp_f32_e32 v87, v14
	v_exp_f32_e32 v88, v18
	v_exp_f32_e32 v89, v20
	v_exp_f32_e32 v90, v22
	v_exp_f32_e32 v91, v24
	v_exp_f32_e32 v92, v26
	v_exp_f32_e32 v93, v28
	v_exp_f32_e32 v94, v30
	v_exp_f32_e32 v95, v31
	v_exp_f32_e32 v96, v32
	s_waitcnt vmcnt(3) lgkmcnt(0)
	s_barrier
	v_cmp_gt_u32_e64 s[6:7], 32, v243
	s_cbranch_vccnz .LBB0_274
	v_mov_b32_e32 v14, v1
	v_mov_b32_e32 v15, v1
	v_mov_b32_e32 v0, v1
	v_mov_b32_e32 v2, v1
	v_mov_b32_e32 v3, v1
	v_mov_b32_e32 v4, v1
	v_mov_b32_e32 v5, v1
	v_mov_b32_e32 v6, v1
	v_mov_b32_e32 v7, v1
	v_mov_b32_e32 v8, v1
	v_mov_b32_e32 v9, v1
	v_mov_b32_e32 v10, v1
	v_mov_b32_e32 v11, v1
	v_mov_b32_e32 v12, v1
	v_mov_b32_e32 v13, v1
	v_mov_b64_e32 v[80:81], v[14:15]
	v_mov_b64_e32 v[64:65], v[14:15]
	v_mov_b64_e32 v[48:49], v[14:15]
	v_mov_b64_e32 v[32:33], v[14:15]
	s_mov_b32 s22, 0
	s_movk_i32 s13, 0x4000
	s_movk_i32 s21, 0x2000
	v_mov_b32_e32 v232, 0
	s_mov_b32 s20, 6
	s_mov_b64 s[14:15], 0
	v_mov_b64_e32 v[78:79], v[12:13]
	v_mov_b64_e32 v[76:77], v[10:11]
	v_mov_b64_e32 v[74:75], v[8:9]
	v_mov_b64_e32 v[72:73], v[6:7]
	v_mov_b64_e32 v[70:71], v[4:5]
	v_mov_b64_e32 v[68:69], v[2:3]
	v_mov_b64_e32 v[66:67], v[0:1]
	v_mov_b64_e32 v[62:63], v[12:13]
	v_mov_b64_e32 v[60:61], v[10:11]
	v_mov_b64_e32 v[58:59], v[8:9]
	v_mov_b64_e32 v[56:57], v[6:7]
	v_mov_b64_e32 v[54:55], v[4:5]
	v_mov_b64_e32 v[52:53], v[2:3]
	v_mov_b64_e32 v[50:51], v[0:1]
	v_mov_b64_e32 v[46:47], v[12:13]
	v_mov_b64_e32 v[44:45], v[10:11]
	v_mov_b64_e32 v[42:43], v[8:9]
	v_mov_b64_e32 v[40:41], v[6:7]
	v_mov_b64_e32 v[38:39], v[4:5]
	v_mov_b64_e32 v[36:37], v[2:3]
	v_mov_b64_e32 v[34:35], v[0:1]
	v_mov_b64_e32 v[30:31], v[12:13]
	v_mov_b64_e32 v[28:29], v[10:11]
	v_mov_b64_e32 v[26:27], v[8:9]
	v_mov_b64_e32 v[24:25], v[6:7]
	v_mov_b64_e32 v[22:23], v[4:5]
	v_mov_b64_e32 v[20:21], v[2:3]
	v_mov_b64_e32 v[18:19], v[0:1]
	v_readfirstlane_b32 s48, v224
	v_readfirstlane_b32 s49, v225
	v_readfirstlane_b32 s50, v226
	v_readfirstlane_b32 s51, v227
	v_readfirstlane_b32 s52, v228
	v_readfirstlane_b32 s53, v229
	s_nop 1
	v_subrev_u32_e32 v208, s48, v224
	v_subrev_u32_e32 v209, s50, v226
.LBB0_260:
	v_add_u32_e32 v0, s22, v251
	ds_read_b64_tr_b16 v[198:199], v0 offset:24576
	ds_read_b64_tr_b16 v[200:201], v0 offset:25088
	s_waitcnt lgkmcnt(9)
	v_mfma_f32_32x32x16_bf16 v[130:145], v[194:197], v[162:165], 0
	v_add_f32_e32 v2, v98, v99
	v_add_f32_e32 v2, v100, v2
	v_add_f32_e32 v2, v101, v2
	v_add_f32_e32 v2, v102, v2
	v_add_f32_e32 v2, v103, v2
	v_cvt_pk_bf16_f32 v150, v98, v99
	v_cvt_pk_bf16_f32 v151, v100, v101
	ds_read_b64_tr_b16 v[194:195], v0 offset:28672
	ds_read_b64_tr_b16 v[196:197], v0 offset:29184
	s_waitcnt lgkmcnt(10)
	v_mfma_f32_32x32x16_bf16 v[114:129], v[186:189], v[162:165], 0
	v_add_f32_e32 v2, v104, v2
	v_add_f32_e32 v2, v105, v2
	v_add_f32_e32 v2, v106, v2
	v_add_f32_e32 v2, v107, v2
	v_cvt_pk_bf16_f32 v152, v102, v103
	v_cvt_pk_bf16_f32 v153, v104, v105
	ds_read_b64_tr_b16 v[102:103], v0 offset:25600
	ds_read_b64_tr_b16 v[104:105], v0 offset:26112
	s_waitcnt lgkmcnt(11)
	v_mfma_f32_32x32x16_bf16 v[130:145], v[190:193], v[158:161], v[130:145]
	v_add_f32_e32 v2, v108, v2
	v_add_f32_e32 v2, v109, v2
	v_add_f32_e32 v2, v110, v2
	v_add_f32_e32 v2, v111, v2
	v_cvt_pk_bf16_f32 v10, v106, v107
	v_cvt_pk_bf16_f32 v11, v108, v109
	ds_read_b64_tr_b16 v[98:99], v0 offset:29696
	ds_read_b64_tr_b16 v[100:101], v0 offset:30208
	s_waitcnt lgkmcnt(12)
	v_mfma_f32_32x32x16_bf16 v[114:129], v[182:185], v[158:161], v[114:129]
	v_add_f32_e32 v2, v112, v2
	v_add_f32_e32 v2, v113, v2
	v_add_f32_e32 v2, v82, v2
	v_add_f32_e32 v2, v83, v2
	v_cvt_pk_bf16_f32 v12, v110, v111
	v_cvt_pk_bf16_f32 v13, v112, v113
	ds_read_b64_tr_b16 v[110:111], v0 offset:26624
	ds_read_b64_tr_b16 v[112:113], v0 offset:27136
	s_waitcnt lgkmcnt(13)
	v_mfma_f32_32x32x16_bf16 v[130:145], v[178:181], v[154:157], v[130:145]
	v_add_f32_e32 v2, v84, v2
	v_add_f32_e32 v2, v85, v2
	v_add_f32_e32 v2, v86, v2
	v_add_f32_e32 v2, v87, v2
	v_cvt_pk_bf16_f32 v6, v82, v83
	v_cvt_pk_bf16_f32 v7, v84, v85
	ds_read_b64_tr_b16 v[106:107], v0 offset:30720
	ds_read_b64_tr_b16 v[108:109], v0 offset:31232
	s_waitcnt lgkmcnt(14)
	v_mfma_f32_32x32x16_bf16 v[114:129], v[174:177], v[154:157], v[114:129]
	v_add_f32_e32 v2, v88, v2
	v_add_f32_e32 v2, v89, v2
	v_add_f32_e32 v2, v90, v2
	v_add_f32_e32 v2, v91, v2
	v_cvt_pk_bf16_f32 v8, v86, v87
	v_cvt_pk_bf16_f32 v9, v88, v89
	ds_read_b64_tr_b16 v[86:87], v0 offset:27648
	ds_read_b64_tr_b16 v[88:89], v0 offset:28160
	s_waitcnt lgkmcnt(14)
	v_mfma_f32_32x32x16_bf16 v[130:145], v[170:173], v[146:149], v[130:145]
	v_add_f32_e32 v2, v92, v2
	v_add_f32_e32 v2, v93, v2
	v_add_f32_e32 v2, v94, v2
	v_add_f32_e32 v14, v95, v2
	v_cvt_pk_bf16_f32 v2, v90, v91
	v_cvt_pk_bf16_f32 v3, v92, v93
	ds_read_b64_tr_b16 v[82:83], v0 offset:31744
	ds_read_b64_tr_b16 v[84:85], v0 offset:32256
	v_mfma_f32_32x32x16_bf16 v[114:129], v[166:169], v[146:149], v[114:129]
	v_add_f32_e32 v0, v96, v14
	v_add_f32_e32 v0, v97, v0
	v_cvt_pk_bf16_f32 v4, v94, v95
	v_cvt_pk_bf16_f32 v5, v96, v97
	s_add_u32 s54, s48, s14
	s_addc_u32 s55, s49, s15
	s_add_u32 s56, s54, 0x8000
	s_addc_u32 s57, s55, 0
	s_add_i32 s16, s21, s43
	s_mov_b32 m0, s16
	s_nop 0
	global_load_lds_dwordx4 v208, s[56:57]
	s_add_u32 s56, s50, s14
	s_addc_u32 s57, s51, s15
	s_add_u32 s56, s56, 0x4000
	s_addc_u32 s57, s57, 0
	s_add_i32 s16, s13, s44
	s_mov_b32 m0, s16
	s_nop 0
	global_load_lds_dwordx4 v209, s[56:57]
	s_add_u32 s58, s52, s14
	s_addc_u32 s59, s53, s15
	s_add_u32 s58, s58, 0x4000
	s_addc_u32 s59, s59, 0
	s_add_i32 s16, s13, s45
	s_mov_b32 m0, s16
	s_nop 0
	global_load_lds_dwordx4 v209, s[58:59]
	v_add_f32_e32 v206, v232, v0
	v_max3_f32 v90, v130, v131, v132
	v_max3_f32 v90, v90, v133, v134
	v_max3_f32 v91, v114, v115, v116
	v_max3_f32 v90, v90, v135, v136
	v_max3_f32 v91, v91, v117, v118
	v_max3_f32 v90, v90, v137, v138
	v_max3_f32 v91, v91, v119, v120
	v_max3_f32 v90, v90, v139, v140
	v_max3_f32 v91, v91, v121, v122
	v_max3_f32 v90, v90, v141, v142
	v_max3_f32 v91, v91, v123, v124
	v_max3_f32 v90, v90, v143, v144
	v_max3_f32 v91, v91, v125, v126
	v_max3_f32 v91, v91, v127, v128
	v_max3_f32 v90, v90, v145, v129
	v_max_f32_e32 v0, v90, v91
	v_mov_b32_e32 v90, v0
	s_nop 1
	v_permlane32_swap_b32_e32 v0, v90
	v_max_f32_e32 v0, v0, v90
	v_sub_f32_e32 v0, v0, v248
	v_cmp_lt_f32_e32 vcc, s84, v0
	s_cmp_lg_u64 vcc, 0
	s_cselect_b64 s[16:17], -1, 0
	s_cbranch_vccnz .LBB0_268

.LBB0_263:
	s_add_i32 s16, s13, 0x2000
	s_cmpk_lg_i32 s13, 0x4000
	s_cselect_b32 s47, s16, 0
	v_add_u32_e32 v207, s21, v251
	ds_read_b64_tr_b16 v[198:199], v207 offset:24576
	ds_read_b64_tr_b16 v[200:201], v207 offset:25088
	s_waitcnt lgkmcnt(9)
	v_mfma_f32_32x32x16_bf16 v[98:113], v[86:89], v[162:165], 0
	v_add_f32_e32 v2, v130, v131
	v_add_f32_e32 v2, v132, v2
	v_add_f32_e32 v2, v133, v2
	v_add_f32_e32 v2, v134, v2
	v_add_f32_e32 v2, v135, v2
	v_cvt_pk_bf16_f32 v150, v130, v131
	v_cvt_pk_bf16_f32 v151, v132, v133
	ds_read_b64_tr_b16 v[194:195], v207 offset:28672
	ds_read_b64_tr_b16 v[196:197], v207 offset:29184
	s_waitcnt lgkmcnt(10)
	v_mfma_f32_32x32x16_bf16 v[82:97], v[82:85], v[162:165], 0
	v_add_f32_e32 v2, v136, v2
	v_add_f32_e32 v2, v137, v2
	v_add_f32_e32 v2, v138, v2
	v_add_f32_e32 v2, v139, v2
	v_cvt_pk_bf16_f32 v152, v134, v135
	v_cvt_pk_bf16_f32 v153, v136, v137
	ds_read_b64_tr_b16 v[190:191], v207 offset:25600
	ds_read_b64_tr_b16 v[192:193], v207 offset:26112
	s_waitcnt lgkmcnt(11)
	v_mfma_f32_32x32x16_bf16 v[98:113], v[186:189], v[158:161], v[98:113]
	v_add_f32_e32 v2, v140, v2
	v_add_f32_e32 v2, v141, v2
	v_add_f32_e32 v2, v142, v2
	v_add_f32_e32 v2, v143, v2
	v_cvt_pk_bf16_f32 v10, v138, v139
	v_cvt_pk_bf16_f32 v11, v140, v141
	ds_read_b64_tr_b16 v[138:139], v207 offset:29696
	ds_read_b64_tr_b16 v[140:141], v207 offset:30208
	s_waitcnt lgkmcnt(12)
	v_mfma_f32_32x32x16_bf16 v[82:97], v[182:185], v[158:161], v[82:97]
	v_add_f32_e32 v2, v144, v2
	v_add_f32_e32 v2, v145, v2
	v_add_f32_e32 v2, v114, v2
	v_add_f32_e32 v2, v115, v2
	v_cvt_pk_bf16_f32 v12, v142, v143
	v_cvt_pk_bf16_f32 v13, v144, v145
	ds_read_b64_tr_b16 v[134:135], v207 offset:26624
	ds_read_b64_tr_b16 v[136:137], v207 offset:27136
	s_waitcnt lgkmcnt(13)
	v_mfma_f32_32x32x16_bf16 v[98:113], v[178:181], v[154:157], v[98:113]
	v_add_f32_e32 v2, v116, v2
	v_add_f32_e32 v2, v117, v2
	v_add_f32_e32 v2, v118, v2
	v_add_f32_e32 v2, v119, v2
	v_cvt_pk_bf16_f32 v6, v114, v115
	v_cvt_pk_bf16_f32 v7, v116, v117
	ds_read_b64_tr_b16 v[130:131], v207 offset:30720
	ds_read_b64_tr_b16 v[132:133], v207 offset:31232
	s_waitcnt lgkmcnt(14)
	v_mfma_f32_32x32x16_bf16 v[82:97], v[174:177], v[154:157], v[82:97]
	v_add_f32_e32 v2, v120, v2
	v_add_f32_e32 v2, v121, v2
	v_add_f32_e32 v2, v122, v2
	v_add_f32_e32 v2, v123, v2
	v_cvt_pk_bf16_f32 v8, v118, v119
	v_cvt_pk_bf16_f32 v9, v120, v121
	ds_read_b64_tr_b16 v[118:119], v207 offset:27648
	ds_read_b64_tr_b16 v[120:121], v207 offset:28160
	s_waitcnt lgkmcnt(14)
	v_mfma_f32_32x32x16_bf16 v[98:113], v[170:173], v[146:149], v[98:113]
	v_add_f32_e32 v2, v124, v2
	v_add_f32_e32 v2, v125, v2
	v_add_f32_e32 v2, v126, v2
	v_add_f32_e32 v142, v127, v2
	v_cvt_pk_bf16_f32 v2, v122, v123
	v_cvt_pk_bf16_f32 v3, v124, v125
	ds_read_b64_tr_b16 v[114:115], v207 offset:31744
	ds_read_b64_tr_b16 v[116:117], v207 offset:32256
	v_mfma_f32_32x32x16_bf16 v[82:97], v[166:169], v[146:149], v[82:97]
	v_add_f32_e32 v4, v128, v142
	v_add_f32_e32 v122, v129, v4
	v_cvt_pk_bf16_f32 v4, v126, v127
	v_cvt_pk_bf16_f32 v5, v128, v129
	s_add_u32 s56, s54, 0xa000
	s_addc_u32 s57, s55, 0
	s_add_i32 s16, s13, s43
	s_mov_b32 m0, s16
	s_nop 0
	global_load_lds_dwordx4 v208, s[56:57]
	s_add_u32 s56, s50, s14
	s_addc_u32 s57, s51, s15
	s_add_u32 s56, s56, 0x6000
	s_addc_u32 s57, s57, 0
	s_add_i32 s16, s47, s44
	s_mov_b32 m0, s16
	s_nop 0
	global_load_lds_dwordx4 v209, s[56:57]
	s_add_u32 s58, s52, s14
	s_addc_u32 s59, s53, s15
	s_add_u32 s58, s58, 0x6000
	s_addc_u32 s59, s59, 0
	s_add_i32 s16, s47, s45
	s_mov_b32 m0, s16
	s_nop 0
	global_load_lds_dwordx4 v209, s[58:59]
	v_max3_f32 v14, v98, v99, v100
	v_max3_f32 v14, v14, v101, v102
	v_max3_f32 v15, v82, v83, v84
	v_max3_f32 v14, v14, v103, v104
	v_max3_f32 v15, v15, v85, v86
	v_max3_f32 v14, v14, v105, v106
	v_max3_f32 v15, v15, v87, v88
	v_max3_f32 v14, v14, v107, v108
	v_max3_f32 v15, v15, v89, v90
	v_max3_f32 v14, v14, v109, v110
	v_max3_f32 v15, v15, v91, v92
	v_max3_f32 v14, v14, v111, v112
	v_max3_f32 v15, v15, v93, v94
	v_max3_f32 v15, v15, v95, v96
	v_max3_f32 v14, v14, v113, v97
	v_max_f32_e32 v14, v14, v15
	v_mov_b32_e32 v15, v14
	s_nop 1
	v_permlane32_swap_b32_e32 v14, v15
	v_max_f32_e32 v14, v14, v15
	v_sub_f32_e32 v14, v14, v248
	v_cmp_lt_f32_e32 vcc, s84, v14
	s_cmp_lg_u64 vcc, 0
	v_add_f32_e32 v232, v206, v122
	s_cselect_b64 s[16:17], -1, 0
	s_cbranch_vccnz .LBB0_271

;   #define WB(a,b) do{ if constexpr(DV2){WAIT_BAR(b);} else {WAIT_BAR(a);} }while(0)
;   #define DMA_K(t,slot) glds16(ksrc+(long)TMAP(t)*KVBLK*PQ,(unsigned)__builtin_amdgcn_readfirstlane(kdst+(slot)))
;   #define DMA_V(t,slot) glds16(vsrc+(long)TMAP(t)*KVBLK*PQ,(unsigned)__builtin_amdgcn_readfirstlane(vdst+(slot)))
;   #define DMA_V2(t,slot) do{ if constexpr(DV2) glds16(v2src+(long)TMAP(t)*KVBLK*PQ,(unsigned)__builtin_amdgcn_readfirstlane(v2dst+(slot))); }while(0)
;     ...
;   int tid=threadIdx.x; asm volatile("":"+v"(tid)); const int lane=tid&63,r32=lane&31,hi=lane>>5; const int wid=__builtin_amdgcn_readfirstlane(tid>>6);
;   const bf16*Qw=Qu+(long)wid*QBLK*PQ;
;   const unsigned lds0=(unsigned)(uintptr_t)shm;
;   float*wsf=(float*)(shm+LDS_WS)+wid*64;
;   const bf16*ksrc=Kh+(long)lane*PQ+wid*8;
;   const bf16*vsrc=Vh+(long)(16*(wid&3)+(lane>>2))*PQ+(wid>>2)*32+(lane&3)*8;
;   const unsigned kdst=lds0+LDS_K+wid*1024, vdst=lds0+LDS_V+wid*1024;
;     ...
;   const bf16*v2src=DV2?V2h+(vsrc-Vh):vsrc; const unsigned v2dst=lds0+LDS_V2+wid*1024;
;     ...
;   const int vb0=(int)(lds0+LDS_V)+((lane>>4)&1)*32+(lane&3)*8+(4*hi+((lane&15)>>2))*64;
;   const char*Kbase=shm+LDS_K; bf16x8 kf[8];
;   const lds_cptr shm3=(lds_cptr)shm; const lds_cptr kp0=shm3+LDS_K+hi*1024+r32*16; const lds_cptr vp0=shm3+LDS_V+((lane>>4)&1)*32+(lane&3)*8+(4*hi+((lane&15)>>2))*64;
;   DMA_K(0,0);DMA_V(0,0);DMA_V2(0,0);DMA_K(1,SLOTB);
;   bf16x8 qr[4];
;   #pragma unroll
;   for(int d0=0;d0<4;++d0)qr[d0]=*reinterpret_cast<const bf16x8*>(&Qw[(long)r32*PQ+d0*16+hi*8]);
;   float mhat=0.f,l_reg=0.f;f32x16 o[ND];
;   #pragma unroll
;   for(int d_=0;d_<ND;++d_)o[d_]=f32x16{};
;   f32x16 negm=f32x16{}; if constexpr(!DV2) asm volatile("":"+v"(negm));
;   const f32x16 zero16=f32x16{};
;     ...
;   const int nq_r=qrow0+(wid>>1), nq_c=(wid&1)*32+r32, n_rsw=min(max(nq_r-4,0),56), n_cs=min(max(nq_c-8,0),48);
;     ...
;   bool resc=false;
;     ...
;   f32x16 pA0,pA1,pB0,pB1;
;   int sl_prev=0,sl_cur=0,sl_next=SLOTB;
;     ...
;   DMA_K(2,2*SLOTB);
;   WB(3,4);
;   qkt(pA0,pA1,Kbase,qr,NEGM,r32,hi);asm volatile("s_nop 15\n\ts_nop 7":"+v"(pA0),"+v"(pA1));CMASK(pA0,pA1,0);
;   START(pA0,pA1);
.LBB0_838:
	s_lshl_b32 s4, s21, 8
	v_mov_b32_e32 v0, 0x100
	s_lshr_b32 s6, s21, 4
	s_and_b32 s22, s4, 0xf00
	v_sub_co_u32_e64 v0, s[4:5], s21, v0
	s_and_b64 s[8:9], s[4:5], exec
	v_readfirstlane_b32 s7, v0
	s_cselect_b32 s23, s6, s7
	v_readlane_b32 s6, v254, 46
	s_lshr_b32 s8, s23, 2
	s_add_i32 s6, s6, s23
	s_add_i32 s11, s22, 0x100
	s_mul_hi_u32 s9, s6, 0x1100
	s_mul_i32 s10, s6, 0x1100
	s_and_b64 s[6:7], s[4:5], exec
	s_cselect_b32 s6, s11, 0
	s_add_u32 s6, s10, s6
	s_addc_u32 s7, s9, 0
	s_lshl_b64 s[6:7], s[6:7], 7
	s_add_u32 s14, s36, s6
	v_readlane_b32 s6, v254, 53
	s_addc_u32 s15, s37, s7
	s_add_i32 s6, s6, s8
	s_mul_i32 s8, s6, 0x88000
	s_mul_hi_u32 s9, s6, 0x88000
	s_add_u32 s6, s38, s8
	s_addc_u32 s7, s39, s9
	s_add_u32 s8, s40, s8
	s_addc_u32 s9, s41, s9
	v_mov_b32_e32 v50, v234
	s_and_b64 s[10:11], s[4:5], exec
	s_cselect_b32 s25, 0x44, 4
	v_readfirstlane_b32 s16, v50
	s_ashr_i32 s10, s16, 6
	s_ashr_i32 s11, s10, 31
	v_and_b32_e32 v17, 63, v50
	s_lshl_b64 s[12:13], s[10:11], 12
	s_add_u32 s12, s14, s12
	v_lshlrev_b32_e32 v0, 7, v17
	s_addc_u32 s13, s15, s13
	v_lshl_add_u64 v[2:3], s[6:7], 0, v[0:1]
	s_lshl_b32 s6, s10, 3
	s_ashr_i32 s7, s6, 31
	v_lshl_add_u64 v[186:187], s[6:7], 1, v[2:3]
	s_lshl_b32 s6, s10, 4
	v_bfe_u32 v0, v50, 2, 4
	v_and_or_b32 v0, s6, 48, v0
	s_ashr_i32 s6, s16, 3
	s_andn2_b32 s6, s6, 31
	s_and_b32 s15, s16, 0x3fffffc0
	v_lshlrev_b32_e32 v0, 7, v0
	s_ashr_i32 s7, s6, 31
	s_lshl_b32 s26, s10, 10
	v_lshl_add_u64 v[2:3], s[8:9], 0, v[0:1]
	v_lshlrev_b32_e32 v196, 3, v50
	s_cmp_lg_u32 0, -1
	v_lshl_add_u64 v[2:3], s[6:7], 1, v[2:3]
	v_and_b32_e32 v199, 24, v196
	s_cselect_b32 s6, 0, 0
	v_and_b32_e32 v197, 31, v50
	v_lshlrev_b32_e32 v0, 1, v199
	s_add_i32 s26, s26, s6
	s_mov_b32 s6, m0
	s_mov_b32 m0, s26
	s_nop 0
	global_load_lds_dwordx4 v[186:187], off
	s_mov_b32 m0, s6
	v_bfe_u32 v198, v50, 5, 1
	v_lshl_add_u64 v[98:99], v[2:3], 0, v[0:1]
	s_add_i32 s27, s26, 0x6000
	s_mov_b32 s6, m0
	s_mov_b32 m0, s27
	s_nop 0
	global_load_lds_dwordx4 v[98:99], off
	s_mov_b32 m0, s6
	v_lshlrev_b32_e32 v0, 7, v197
	v_lshl_add_u64 v[2:3], v[186:187], 0, s[86:87]
	s_add_i32 s6, s26, 0x2000
	s_mov_b32 s7, m0
	s_mov_b32 m0, s6
	s_nop 0
	global_load_lds_dwordx4 v[2:3], off
	s_mov_b32 m0, s7
	v_lshl_or_b32 v0, v198, 4, v0
	global_load_dwordx4 v[146:149], v0, s[12:13]
	global_load_dwordx4 v[142:145], v0, s[12:13] offset:32
	global_load_dwordx4 v[138:141], v0, s[12:13] offset:64
	global_load_dwordx4 v[130:133], v0, s[12:13] offset:96
	v_mov_b32_e32 v14, v1
	v_mov_b32_e32 v15, v1
	v_lshlrev_b32_e32 v0, 10, v198
	v_lshlrev_b32_e32 v18, 4, v197
	v_mov_b32_e32 v2, v1
	v_mov_b32_e32 v3, v1
	v_mov_b32_e32 v4, v1
	v_mov_b32_e32 v5, v1
	v_mov_b32_e32 v6, v1
	v_mov_b32_e32 v7, v1
	v_mov_b32_e32 v8, v1
	v_mov_b32_e32 v9, v1
	v_mov_b32_e32 v10, v1
	v_mov_b32_e32 v11, v1
	v_mov_b32_e32 v12, v1
	v_mov_b32_e32 v13, v1
	v_add3_u32 v203, 0, v0, v18
	v_mov_b32_e32 v0, v1
	v_mov_b64_e32 v[32:33], v[14:15]
	v_mov_b64_e32 v[30:31], v[12:13]
	v_mov_b64_e32 v[28:29], v[10:11]
	v_mov_b64_e32 v[26:27], v[8:9]
	v_mov_b64_e32 v[24:25], v[6:7]
	v_mov_b64_e32 v[22:23], v[4:5]
	v_mov_b64_e32 v[20:21], v[2:3]
	v_mov_b64_e32 v[18:19], v[0:1]
	v_lshl_add_u64 v[34:35], v[186:187], 0, s[96:97]
	s_add_i32 s6, s26, 0x4000
	s_mov_b32 s7, m0
	s_mov_b32 m0, s6
	s_nop 0
	global_load_lds_dwordx4 v[34:35], off
	s_mov_b32 m0, s7
	s_waitcnt vmcnt(3) lgkmcnt(0)
	s_barrier
	ds_read_b128 v[2:5], v203
	ds_read_b128 v[6:9], v203 offset:512
	v_lshlrev_b32_e32 v0, 1, v50
	v_and_b32_e32 v201, 32, v0
	s_lshl_b32 s6, s15, 2
	s_waitcnt vmcnt(3) lgkmcnt(1)
	v_mfma_f32_32x32x16_bf16 v[34:49], v[2:5], v[146:149], v[18:33]
	s_add_i32 s24, s6, 0
	s_mov_b32 s14, 0
	s_mov_b32 s82, 1
	s_movk_i32 s28, 0x2000
	s_movk_i32 s29, 0x4000
	s_andn2_b64 vcc, exec, s[4:5]
	v_lshlrev_b32_e32 v205, 4, v198
	s_waitcnt lgkmcnt(0)
	v_mfma_f32_32x32x16_bf16 v[18:33], v[6:9], v[146:149], v[18:33]
	ds_read_b128 v[2:5], v203 offset:2048
	ds_read_b128 v[6:9], v203 offset:2560
	v_lshl_add_u32 v200, v197, 2, s24
	s_waitcnt vmcnt(2) lgkmcnt(1)
	v_mfma_f32_32x32x16_bf16 v[34:49], v[2:5], v[142:145], v[34:49]
	s_waitcnt lgkmcnt(0)
	v_mfma_f32_32x32x16_bf16 v[18:33], v[6:9], v[142:145], v[18:33]
	ds_read_b128 v[2:5], v203 offset:4096
	ds_read_b128 v[6:9], v203 offset:4608
	s_waitcnt vmcnt(1) lgkmcnt(1)
	v_mfma_f32_32x32x16_bf16 v[34:49], v[2:5], v[138:141], v[34:49]
	ds_read_b128 v[2:5], v203 offset:6144
	s_waitcnt lgkmcnt(1)
	v_mfma_f32_32x32x16_bf16 v[18:33], v[6:9], v[138:141], v[18:33]
	ds_read_b128 v[6:9], v203 offset:6656
	s_waitcnt vmcnt(0) lgkmcnt(1)
	v_mfma_f32_32x32x16_bf16 v[34:49], v[2:5], v[130:133], v[34:49]
	v_lshlrev_b32_e32 v2, 4, v50
	v_and_b32_e32 v0, 0xc0, v2
	v_lshl_or_b32 v0, v198, 8, v0
	v_add_u32_e32 v2, 0, v201
	v_add3_u32 v204, v2, v199, v0
	s_waitcnt lgkmcnt(0)
	v_mfma_f32_32x32x16_bf16 v[18:33], v[6:9], v[130:133], v[18:33]
	s_nop 15
	s_nop 7
	s_nop 0
	v_max3_f32 v3, v34, v35, v18
	v_max3_f32 v4, v36, v37, v19
	s_nop 0
	v_max3_f32 v3, v3, v20, v21
	v_max3_f32 v4, v4, v40, v41
	s_nop 0
	v_max3_f32 v3, v3, v38, v39
	v_max3_f32 v4, v4, v24, v25
	s_nop 0
	v_max3_f32 v3, v3, v22, v23
	v_max3_f32 v4, v4, v44, v45
	s_nop 0
	v_max3_f32 v3, v3, v42, v43
	v_max3_f32 v4, v4, v28, v29
	s_nop 0
	v_max3_f32 v3, v3, v26, v27
	v_max3_f32 v4, v4, v48, v49
	s_nop 0
	v_max3_f32 v3, v3, v46, v47
	v_max3_f32 v4, v4, v32, v33
	s_nop 0
	v_max3_f32 v3, v3, v30, v31
	s_nop 0
	v_max_f32_e32 v3, v3, v4
	s_nop 0
	v_mov_b32_e32 v4, v3
	s_nop 1
	v_permlane32_swap_b32_e32 v3, v4
	v_max_f32_e32 v3, v3, v4
	s_nop 0
	v_add_f32_e32 v202, v1, v3
	v_sub_f32_e32 v4, v34, v3
	v_sub_f32_e32 v5, v18, v3
	v_sub_f32_e32 v6, v35, v3
	v_sub_f32_e32 v7, v19, v3
	v_sub_f32_e32 v8, v36, v3
	s_nop 0
	v_xor_b32_e32 v50, 0x80000000, v202
	v_mov_b32_e32 v51, v50
	v_mov_b32_e32 v52, v50
	v_mov_b32_e32 v53, v50
	v_mov_b32_e32 v54, v50
	v_mov_b32_e32 v55, v50
	v_mov_b32_e32 v56, v50
	v_mov_b32_e32 v57, v50
	v_mov_b32_e32 v58, v50
	v_mov_b32_e32 v59, v50
	v_mov_b32_e32 v60, v50
	v_mov_b32_e32 v61, v50
	v_mov_b32_e32 v62, v50
	v_mov_b32_e32 v63, v50
	v_mov_b32_e32 v64, v50
	v_mov_b32_e32 v65, v50
	v_sub_f32_e32 v9, v20, v3
	v_sub_f32_e32 v10, v37, v3
	v_sub_f32_e32 v11, v21, v3
	v_sub_f32_e32 v12, v38, v3
	v_sub_f32_e32 v13, v22, v3
	v_sub_f32_e32 v14, v39, v3
	v_sub_f32_e32 v15, v23, v3
	v_sub_f32_e32 v18, v40, v3
	v_sub_f32_e32 v19, v24, v3
	v_sub_f32_e32 v20, v41, v3
	v_sub_f32_e32 v21, v25, v3
	v_sub_f32_e32 v22, v42, v3
	v_sub_f32_e32 v23, v26, v3
	v_sub_f32_e32 v24, v43, v3
	v_sub_f32_e32 v25, v27, v3
	v_sub_f32_e32 v26, v44, v3
	v_sub_f32_e32 v27, v28, v3
	v_sub_f32_e32 v28, v45, v3
	v_sub_f32_e32 v29, v29, v3
	v_sub_f32_e32 v34, v46, v3
	v_sub_f32_e32 v30, v30, v3
	v_sub_f32_e32 v35, v47, v3
	v_sub_f32_e32 v31, v31, v3
	v_sub_f32_e32 v36, v48, v3
	v_sub_f32_e32 v32, v32, v3
	v_sub_f32_e32 v37, v49, v3
	v_sub_f32_e32 v3, v33, v3
	s_waitcnt vmcnt(0) lgkmcnt(0)
	s_barrier
; #define WAIT_BAR(N) asm volatile("s_waitcnt vmcnt(" #N ") lgkmcnt(0)\n\ts_barrier":::"memory")
;   #define WB(a,b) do{ if constexpr(DV2){WAIT_BAR(b);} else {WAIT_BAR(a);} }while(0)
;   #define DMA_K(t,slot) glds16(ksrc+(long)TMAP(t)*KVBLK*PQ,(unsigned)__builtin_amdgcn_readfirstlane(kdst+(slot)))
;   #define DMA_V(t,slot) glds16(vsrc+(long)TMAP(t)*KVBLK*PQ,(unsigned)__builtin_amdgcn_readfirstlane(vdst+(slot)))
;   #define DMA_V2(t,slot) do{ if constexpr(DV2) glds16(v2src+(long)TMAP(t)*KVBLK*PQ,(unsigned)__builtin_amdgcn_readfirstlane(v2dst+(slot))); }while(0)
;   #define ROT() do{sl_prev=sl_cur;sl_cur=sl_next;sl_next=(sl_next==(NSLOT-1)*SLOTB)?0:sl_next+SLOTB;}while(0)
;     ...
;   START(pA0,pA1);
;   _Pragma("unroll") for(int r=0;r<16;++r)pA1[r]=__builtin_amdgcn_exp2f(pA1[r]);
;   WAIT_BAR(0);
;   DMA_K(3,0);DMA_V(1,SLOTB);DMA_V2(1,SLOTB);
;   ROT();
;   kload8(kf,kp0+sl_cur);
;   WB(2,3);
;   s16x4 vlo[8],vhi[8]; u32x4 pw0,pw1,pw2,pw3;
	s_nop 0
	v_exp_f32_e32 v87, v14
	v_exp_f32_e32 v81, v3
	v_lshl_add_u64 v[2:3], v[186:187], 0, s[0:1]
	s_mov_b32 s6, m0
	s_mov_b32 m0, s26
	s_nop 0
	global_load_lds_dwordx4 v[2:3], off
	s_mov_b32 m0, s6
	v_exp_f32_e32 v71, v15
	v_lshl_add_u64 v[14:15], v[98:99], 0, s[86:87]
	s_add_i32 s6, s26, 0x8000
	s_mov_b32 s7, m0
	s_mov_b32 m0, s6
	s_nop 0
	global_load_lds_dwordx4 v[14:15], off
	s_mov_b32 m0, s7
	ds_read_b128 v[178:181], v203 offset:8192
	ds_read_b128 v[174:177], v203 offset:8704
	ds_read_b128 v[170:173], v203 offset:10240
	ds_read_b128 v[166:169], v203 offset:10752
	ds_read_b128 v[162:165], v203 offset:12288
	ds_read_b128 v[158:161], v203 offset:12800
	ds_read_b128 v[154:157], v203 offset:14336
	ds_read_b128 v[150:153], v203 offset:14848
	v_exp_f32_e32 v82, v4
	v_exp_f32_e32 v83, v6
	v_exp_f32_e32 v84, v8
	v_exp_f32_e32 v85, v10
	v_exp_f32_e32 v86, v12
	v_exp_f32_e32 v88, v18
	v_exp_f32_e32 v89, v20
	v_exp_f32_e32 v90, v22
	v_exp_f32_e32 v91, v24
	v_exp_f32_e32 v92, v26
	v_exp_f32_e32 v93, v28
	v_exp_f32_e32 v94, v34
	v_exp_f32_e32 v95, v35
	v_exp_f32_e32 v96, v36
	v_exp_f32_e32 v97, v37
	v_exp_f32_e32 v66, v5
	v_exp_f32_e32 v67, v7
	v_exp_f32_e32 v68, v9
	v_exp_f32_e32 v69, v11
	v_exp_f32_e32 v70, v13
	v_exp_f32_e32 v72, v19
	v_exp_f32_e32 v73, v21
	v_exp_f32_e32 v74, v23
	v_exp_f32_e32 v75, v25
	v_exp_f32_e32 v76, v27
	v_exp_f32_e32 v77, v29
	v_exp_f32_e32 v78, v30
	v_exp_f32_e32 v79, v31
	v_exp_f32_e32 v80, v32
	s_waitcnt vmcnt(2) lgkmcnt(0)
	s_barrier
	v_cmp_gt_u32_e64 s[6:7], 32, v17
	s_cbranch_vccnz .LBB0_854
	v_mov_b32_e32 v206, 0
	v_lshl_add_u64 v[188:189], v[98:99], 0, s[0:1]
	v_lshl_add_u64 v[190:191], v[186:187], 0, s[2:3]
	s_movk_i32 s14, 0x4000
	s_movk_i32 s16, 0x2000
	s_mov_b32 s8, 0
	s_mov_b32 s15, 6
	v_mov_b32_e32 v34, 0
	v_mov_b32_e32 v35, v206
	v_mov_b32_e32 v36, v206
	v_mov_b32_e32 v37, v206
	v_mov_b32_e32 v38, v206
	v_mov_b32_e32 v39, v206
	v_mov_b32_e32 v40, v206
	v_mov_b32_e32 v41, v206
	v_mov_b32_e32 v42, v206
	v_mov_b32_e32 v43, v206
	v_mov_b32_e32 v44, v206
	v_mov_b32_e32 v45, v206
	v_mov_b32_e32 v46, v206
	v_mov_b32_e32 v47, v206
	v_mov_b32_e32 v48, v206
	v_mov_b32_e32 v49, v206
	v_mov_b32_e32 v18, v206
	v_mov_b32_e32 v19, v206
	v_mov_b32_e32 v20, v206
	v_mov_b32_e32 v21, v206
	v_mov_b32_e32 v22, v206
	v_mov_b32_e32 v23, v206
	v_mov_b32_e32 v24, v206
	v_mov_b32_e32 v25, v206
	v_mov_b32_e32 v26, v206
	v_mov_b32_e32 v27, v206
	v_mov_b32_e32 v28, v206
	v_mov_b32_e32 v29, v206
	v_mov_b32_e32 v30, v206
	v_mov_b32_e32 v31, v206
	v_mov_b32_e32 v32, v206
	v_mov_b32_e32 v33, v206
	v_readfirstlane_b32 s34, v190
	v_readfirstlane_b32 s35, v191
	v_readfirstlane_b32 s36, v188
	v_readfirstlane_b32 s37, v189
	v_mov_b32_e32 v209, 0
	v_mov_b32_e32 v211, 0
	s_nop 1
	v_subrev_u32_e32 v208, s34, v190
	v_subrev_u32_e32 v210, s36, v188
.LBB0_840:
	v_add_u32_e32 v192, s8, v204
	ds_read_b64_tr_b16 v[182:183], v192 offset:24576
	ds_read_b64_tr_b16 v[184:185], v192 offset:25088
	s_waitcnt lgkmcnt(9)
	v_mfma_f32_32x32x16_bf16 v[114:129], v[178:181], v[146:149], v[50:65]
	v_add_f32_e32 v2, v82, v83
	v_add_f32_e32 v2, v84, v2
	v_add_f32_e32 v2, v85, v2
	v_add_f32_e32 v2, v86, v2
	v_add_f32_e32 v2, v87, v2
	v_cvt_pk_bf16_f32 v134, v82, v83
	v_cvt_pk_bf16_f32 v135, v84, v85
	ds_read_b64_tr_b16 v[178:179], v192 offset:28672
	ds_read_b64_tr_b16 v[180:181], v192 offset:29184
	s_waitcnt lgkmcnt(10)
	v_mfma_f32_32x32x16_bf16 v[98:113], v[174:177], v[146:149], v[50:65]
	v_add_f32_e32 v2, v88, v2
	v_add_f32_e32 v2, v89, v2
	v_add_f32_e32 v2, v90, v2
	v_add_f32_e32 v2, v91, v2
	v_cvt_pk_bf16_f32 v136, v86, v87
	v_cvt_pk_bf16_f32 v137, v88, v89
	ds_read_b64_tr_b16 v[82:83], v192 offset:25600
	ds_read_b64_tr_b16 v[84:85], v192 offset:26112
	s_waitcnt lgkmcnt(11)
	v_mfma_f32_32x32x16_bf16 v[114:129], v[170:173], v[142:145], v[114:129]
	v_add_f32_e32 v2, v92, v2
	v_add_f32_e32 v2, v93, v2
	v_add_f32_e32 v2, v94, v2
	v_add_f32_e32 v2, v95, v2
	v_cvt_pk_bf16_f32 v10, v90, v91
	v_cvt_pk_bf16_f32 v11, v92, v93
	ds_read_b64_tr_b16 v[86:87], v192 offset:29696
	ds_read_b64_tr_b16 v[88:89], v192 offset:30208
	s_waitcnt lgkmcnt(12)
	v_mfma_f32_32x32x16_bf16 v[98:113], v[166:169], v[142:145], v[98:113]
	v_add_f32_e32 v2, v96, v2
	v_add_f32_e32 v2, v97, v2
	v_add_f32_e32 v2, v66, v2
	v_add_f32_e32 v2, v67, v2
	v_cvt_pk_bf16_f32 v12, v94, v95
	v_cvt_pk_bf16_f32 v13, v96, v97
	ds_read_b64_tr_b16 v[90:91], v192 offset:26624
	ds_read_b64_tr_b16 v[92:93], v192 offset:27136
	s_waitcnt lgkmcnt(13)
	v_mfma_f32_32x32x16_bf16 v[114:129], v[162:165], v[138:141], v[114:129]
	v_add_f32_e32 v2, v68, v2
	v_add_f32_e32 v2, v69, v2
	v_add_f32_e32 v2, v70, v2
	v_add_f32_e32 v2, v71, v2
	v_cvt_pk_bf16_f32 v6, v66, v67
	v_cvt_pk_bf16_f32 v7, v68, v69
	ds_read_b64_tr_b16 v[66:67], v192 offset:30720
	ds_read_b64_tr_b16 v[68:69], v192 offset:31232
	s_waitcnt lgkmcnt(14)
	v_mfma_f32_32x32x16_bf16 v[98:113], v[158:161], v[138:141], v[98:113]
	v_add_f32_e32 v2, v72, v2
	v_add_f32_e32 v2, v73, v2
	v_add_f32_e32 v2, v74, v2
	v_add_f32_e32 v2, v75, v2
	v_cvt_pk_bf16_f32 v8, v70, v71
	v_cvt_pk_bf16_f32 v9, v72, v73
	ds_read_b64_tr_b16 v[70:71], v192 offset:27648
	ds_read_b64_tr_b16 v[72:73], v192 offset:28160
	s_waitcnt lgkmcnt(14)
	v_mfma_f32_32x32x16_bf16 v[114:129], v[154:157], v[130:133], v[114:129]
	v_add_f32_e32 v2, v76, v2
	v_add_f32_e32 v2, v77, v2
	v_add_f32_e32 v2, v78, v2
	v_add_f32_e32 v94, v79, v2
	v_cvt_pk_bf16_f32 v2, v74, v75
	v_cvt_pk_bf16_f32 v3, v76, v77
	ds_read_b64_tr_b16 v[74:75], v192 offset:31744
	ds_read_b64_tr_b16 v[76:77], v192 offset:32256
	v_mfma_f32_32x32x16_bf16 v[98:113], v[150:153], v[130:133], v[98:113]
	v_add_f32_e32 v4, v80, v94
	v_add_f32_e32 v94, v81, v4
	v_cvt_pk_bf16_f32 v4, v78, v79
	v_cvt_pk_bf16_f32 v5, v80, v81
	s_add_u32 s38, s34, s52
	s_addc_u32 s39, s35, s53
	s_add_i32 s8, s16, s26
	s_mov_b32 m0, s8
	s_nop 0
	global_load_lds_dwordx4 v208, s[38:39]
	s_add_u32 s40, s36, s52
	s_addc_u32 s41, s37, s53
	s_add_i32 s8, s14, s27
	s_mov_b32 m0, s8
	s_nop 0
	global_load_lds_dwordx4 v210, s[40:41]
	v_max3_f32 v78, v114, v115, v116
	v_max3_f32 v78, v78, v117, v118
	v_max3_f32 v79, v98, v99, v100
	v_max3_f32 v78, v78, v119, v120
	v_max3_f32 v79, v79, v101, v102
	v_max3_f32 v78, v78, v121, v122
	v_max3_f32 v79, v79, v103, v104
	v_max3_f32 v78, v78, v123, v124
	v_max3_f32 v79, v79, v105, v106
	v_max3_f32 v78, v78, v125, v126
	v_max3_f32 v79, v79, v107, v108
	v_max3_f32 v78, v78, v127, v128
	v_max3_f32 v79, v79, v109, v110
	v_max3_f32 v79, v79, v111, v112
	v_max3_f32 v78, v78, v129, v113
	v_max_f32_e32 v78, v78, v79
	v_mov_b32_e32 v79, v78
	s_nop 1
	v_permlane32_swap_b32_e32 v78, v79
	v_max_f32_e32 v78, v78, v79
	v_cmp_lt_f32_e32 vcc, s84, v78
	s_cmp_lg_u64 vcc, 0
	v_add_f32_e32 v192, v206, v94
	s_cselect_b64 s[8:9], -1, 0
	s_cbranch_vccnz .LBB0_848
.LBB0_841:
	s_waitcnt lgkmcnt(14)
	v_mfma_f32_32x32x16_bf16 v[34:49], v[134:137], v[182:185], v[34:49]
	v_exp_f32_e32 v114, v114
	v_exp_f32_e32 v115, v115
	v_exp_f32_e32 v116, v116
	v_exp_f32_e32 v117, v117
	s_waitcnt lgkmcnt(12)
	v_mfma_f32_32x32x16_bf16 v[18:33], v[134:137], v[178:181], v[18:33]
	v_exp_f32_e32 v118, v118
	v_exp_f32_e32 v119, v119
	v_exp_f32_e32 v120, v120
	v_exp_f32_e32 v121, v121
	v_add_u32_e32 v94, s14, v203
	ds_read_b128 v[78:81], v94
	ds_read_b128 v[178:181], v94 offset:512
	s_waitcnt lgkmcnt(12)
	v_mfma_f32_32x32x16_bf16 v[34:49], v[10:13], v[82:85], v[34:49]
	v_exp_f32_e32 v122, v122
	v_exp_f32_e32 v123, v123
	v_exp_f32_e32 v124, v124
	v_exp_f32_e32 v125, v125
	ds_read_b128 v[182:185], v94 offset:2048
	ds_read_b128 v[174:177], v94 offset:2560
	s_waitcnt lgkmcnt(12)
	v_mfma_f32_32x32x16_bf16 v[18:33], v[10:13], v[86:89], v[18:33]
	v_exp_f32_e32 v126, v126
	v_exp_f32_e32 v127, v127
	v_exp_f32_e32 v128, v128
	v_exp_f32_e32 v129, v129
	ds_read_b128 v[170:173], v94 offset:4096
	ds_read_b128 v[166:169], v94 offset:4608
	s_waitcnt lgkmcnt(12)
	v_mfma_f32_32x32x16_bf16 v[34:49], v[6:9], v[90:93], v[34:49]
	v_exp_f32_e32 v98, v98
	v_exp_f32_e32 v99, v99
	v_exp_f32_e32 v100, v100
	v_exp_f32_e32 v101, v101
	ds_read_b128 v[162:165], v94 offset:6144
	ds_read_b128 v[158:161], v94 offset:6656
	s_waitcnt lgkmcnt(12)
	v_mfma_f32_32x32x16_bf16 v[18:33], v[6:9], v[66:69], v[18:33]
	v_exp_f32_e32 v102, v102
	v_exp_f32_e32 v103, v103
	v_exp_f32_e32 v104, v104
	v_exp_f32_e32 v105, v105
	s_waitcnt lgkmcnt(10)
	v_mfma_f32_32x32x16_bf16 v[34:49], v[2:5], v[70:73], v[34:49]
	v_exp_f32_e32 v106, v106
	v_exp_f32_e32 v107, v107
	v_exp_f32_e32 v108, v108
	v_exp_f32_e32 v109, v109
	s_waitcnt lgkmcnt(8)
	v_mfma_f32_32x32x16_bf16 v[18:33], v[2:5], v[74:77], v[18:33]
	v_exp_f32_e32 v110, v110
	v_exp_f32_e32 v111, v111
	v_exp_f32_e32 v112, v112
	v_exp_f32_e32 v113, v113
	s_waitcnt vmcnt(2) lgkmcnt(0)
	s_barrier
	s_andn2_b64 vcc, exec, s[8:9]
	s_cbranch_vccnz .LBB0_843
	s_waitcnt lgkmcnt(0)
	v_add_u32_e32 v193, s24, v205
	ds_read_b128 v[66:69], v193 offset:49248
	ds_read_b128 v[70:73], v193 offset:49216
	ds_read_b128 v[74:77], v193 offset:49184
	ds_read_b128 v[82:85], v193 offset:49152
	s_waitcnt lgkmcnt(3)
	v_pk_mul_f32 v[46:47], v[46:47], v[66:67]
	s_waitcnt lgkmcnt(2)
	v_pk_mul_f32 v[42:43], v[42:43], v[70:71]
	s_waitcnt lgkmcnt(1)
	v_pk_mul_f32 v[38:39], v[38:39], v[74:75]
	v_pk_mul_f32 v[48:49], v[48:49], v[68:69]
	v_pk_mul_f32 v[44:45], v[44:45], v[72:73]
	v_pk_mul_f32 v[40:41], v[40:41], v[76:77]
	s_waitcnt lgkmcnt(0)
	v_pk_mul_f32 v[36:37], v[36:37], v[84:85]
	v_pk_mul_f32 v[34:35], v[34:35], v[82:83]
	v_pk_mul_f32 v[30:31], v[30:31], v[66:67]
	v_pk_mul_f32 v[26:27], v[26:27], v[70:71]
	v_pk_mul_f32 v[22:23], v[22:23], v[74:75]
	v_pk_mul_f32 v[32:33], v[32:33], v[68:69]
	v_pk_mul_f32 v[28:29], v[28:29], v[72:73]
	v_pk_mul_f32 v[24:25], v[24:25], v[76:77]
	v_pk_mul_f32 v[20:21], v[20:21], v[84:85]
	v_pk_mul_f32 v[18:19], v[18:19], v[82:83]
.LBB0_843:
	s_add_i32 s8, s14, 0x2000
	s_cmpk_lg_i32 s14, 0x4000
	s_cselect_b32 s28, s8, 0
	v_add_u32_e32 v194, s16, v204
	ds_read_b64_tr_b16 v[154:155], v194 offset:24576
	ds_read_b64_tr_b16 v[156:157], v194 offset:25088
	s_waitcnt lgkmcnt(9)
	v_mfma_f32_32x32x16_bf16 v[82:97], v[78:81], v[146:149], v[50:65]
	v_add_f32_e32 v2, v114, v115
	v_add_f32_e32 v2, v116, v2
	v_add_f32_e32 v2, v117, v2
	v_add_f32_e32 v2, v118, v2
	v_add_f32_e32 v2, v119, v2
	v_cvt_pk_bf16_f32 v134, v114, v115
	v_cvt_pk_bf16_f32 v135, v116, v117
	ds_read_b64_tr_b16 v[150:151], v194 offset:28672
	ds_read_b64_tr_b16 v[152:153], v194 offset:29184
	s_waitcnt lgkmcnt(10)
	v_mfma_f32_32x32x16_bf16 v[66:81], v[178:181], v[146:149], v[50:65]
	v_add_f32_e32 v2, v120, v2
	v_add_f32_e32 v2, v121, v2
	v_add_f32_e32 v2, v122, v2
	v_add_f32_e32 v2, v123, v2
	v_cvt_pk_bf16_f32 v136, v118, v119
	v_cvt_pk_bf16_f32 v137, v120, v121
	ds_read_b64_tr_b16 v[114:115], v194 offset:25600
	ds_read_b64_tr_b16 v[116:117], v194 offset:26112
	s_waitcnt lgkmcnt(11)
	v_mfma_f32_32x32x16_bf16 v[82:97], v[182:185], v[142:145], v[82:97]
	v_add_f32_e32 v2, v124, v2
	v_add_f32_e32 v2, v125, v2
	v_add_f32_e32 v2, v126, v2
	v_add_f32_e32 v2, v127, v2
	v_cvt_pk_bf16_f32 v10, v122, v123
	v_cvt_pk_bf16_f32 v11, v124, v125
	ds_read_b64_tr_b16 v[118:119], v194 offset:29696
	ds_read_b64_tr_b16 v[120:121], v194 offset:30208
	s_waitcnt lgkmcnt(12)
	v_mfma_f32_32x32x16_bf16 v[66:81], v[174:177], v[142:145], v[66:81]
	v_add_f32_e32 v2, v128, v2
	v_add_f32_e32 v2, v129, v2
	v_add_f32_e32 v2, v98, v2
	v_add_f32_e32 v2, v99, v2
	v_cvt_pk_bf16_f32 v12, v126, v127
	v_cvt_pk_bf16_f32 v13, v128, v129
	ds_read_b64_tr_b16 v[122:123], v194 offset:26624
	ds_read_b64_tr_b16 v[124:125], v194 offset:27136
	s_waitcnt lgkmcnt(13)
	v_mfma_f32_32x32x16_bf16 v[82:97], v[170:173], v[138:141], v[82:97]
	v_add_f32_e32 v2, v100, v2
	v_add_f32_e32 v2, v101, v2
	v_add_f32_e32 v2, v102, v2
	v_add_f32_e32 v2, v103, v2
	v_cvt_pk_bf16_f32 v6, v98, v99
	v_cvt_pk_bf16_f32 v7, v100, v101
	ds_read_b64_tr_b16 v[98:99], v194 offset:30720
	ds_read_b64_tr_b16 v[100:101], v194 offset:31232
	s_waitcnt lgkmcnt(14)
	v_mfma_f32_32x32x16_bf16 v[66:81], v[166:169], v[138:141], v[66:81]
	v_add_f32_e32 v2, v104, v2
	v_add_f32_e32 v2, v105, v2
	v_add_f32_e32 v2, v106, v2
	v_add_f32_e32 v2, v107, v2
	v_cvt_pk_bf16_f32 v8, v102, v103
	v_cvt_pk_bf16_f32 v9, v104, v105
	ds_read_b64_tr_b16 v[102:103], v194 offset:27648
	ds_read_b64_tr_b16 v[104:105], v194 offset:28160
	s_waitcnt lgkmcnt(14)
	v_mfma_f32_32x32x16_bf16 v[82:97], v[162:165], v[130:133], v[82:97]
	v_add_f32_e32 v2, v108, v2
	v_add_f32_e32 v2, v109, v2
	v_add_f32_e32 v2, v110, v2
	v_add_f32_e32 v126, v111, v2
	v_cvt_pk_bf16_f32 v2, v106, v107
	v_cvt_pk_bf16_f32 v3, v108, v109
	ds_read_b64_tr_b16 v[106:107], v194 offset:31744
	ds_read_b64_tr_b16 v[108:109], v194 offset:32256
	v_mfma_f32_32x32x16_bf16 v[66:81], v[158:161], v[130:133], v[66:81]
	v_add_f32_e32 v4, v112, v126
	v_add_f32_e32 v126, v113, v4
	v_cvt_pk_bf16_f32 v4, v110, v111
	v_cvt_pk_bf16_f32 v5, v112, v113
	s_add_i32 s8, s14, s26
	s_mov_b32 m0, s8
	s_nop 0
	global_load_lds_dwordx4 v208, s[34:35]
	s_add_i32 s8, s28, s27
	s_mov_b32 m0, s8
	s_nop 0
	global_load_lds_dwordx4 v210, s[36:37]
	v_max3_f32 v110, v82, v83, v84
	v_max3_f32 v110, v110, v85, v86
	v_max3_f32 v111, v66, v67, v68
	v_max3_f32 v110, v110, v87, v88
	v_max3_f32 v111, v111, v69, v70
	v_max3_f32 v110, v110, v89, v90
	v_max3_f32 v111, v111, v71, v72
	v_max3_f32 v110, v110, v91, v92
	v_max3_f32 v111, v111, v73, v74
	v_max3_f32 v110, v110, v93, v94
	v_max3_f32 v111, v111, v75, v76
	v_max3_f32 v110, v110, v95, v96
	v_max3_f32 v111, v111, v77, v78
	v_max3_f32 v111, v111, v79, v80
	v_max3_f32 v110, v110, v97, v81
	v_max_f32_e32 v110, v110, v111
	v_mov_b32_e32 v111, v110
	s_nop 1
	v_permlane32_swap_b32_e32 v110, v111
	v_max_f32_e32 v110, v110, v111
	v_cmp_lt_f32_e32 vcc, s84, v110
	s_cmp_lg_u64 vcc, 0
	v_add_f32_e32 v206, v192, v126
	s_cselect_b64 s[8:9], -1, 0
	s_cbranch_vccnz .LBB0_851
;   #define WB(a,b) do{ if constexpr(DV2){WAIT_BAR(b);} else {WAIT_BAR(a);} }while(0)
;   #define RESC() do{ if(resc){ asm volatile("s_waitcnt lgkmcnt(0)":::"memory"); \
;       _Pragma("unroll") for(int d_=0;d_<ND;++d_) _Pragma("unroll") for(int r=0;r<16;++r)o[d_][r]*=wsf[crow(r,hi)]; } }while(0)
;   #define ROT() do{sl_prev=sl_cur;sl_cur=sl_next;sl_next=(sl_next==(NSLOT-1)*SLOTB)?0:sl_next+SLOTB;}while(0)
;   #define ENDW(tt) do{ if((tt)+3<NT){WB(2,3);} else if((tt)+2<NT){WB(1,2);} else {WAIT_BAR(0);} }while(0)
;     ...
;   int t=1;
;   for(;t+5<NT;t+=2){
;     STEP(pB0,pB1,pA0,pA1,t,true,true,true);     WB(2,3); RESC(); ROT();
;     STEP(pA0,pA1,pB0,pB1,t+1,true,true,true);   WB(2,3); RESC(); ROT();
;   }
;     ...
;   for(;t+1<NT;t+=2){
;     STEP(pB0,pB1,pA0,pA1,t,(t+3<NT),(t+1<NT),(t+1<NT));       ENDW(t);   RESC(); ROT();
;     STEP(pA0,pA1,pB0,pB1,t+1,(t+4<NT),(t+2<NT),(t+2<NT));     ENDW(t+1); RESC(); ROT();
;   }
;   STEP(pB0,pB1,pA0,pA1,NT-1,false,false,false); RESC();
.LBB0_844:
	s_waitcnt lgkmcnt(14)
	v_mfma_f32_32x32x16_bf16 v[34:49], v[134:137], v[154:157], v[34:49]
	v_exp_f32_e32 v82, v82
	v_exp_f32_e32 v83, v83
	v_exp_f32_e32 v84, v84
	v_exp_f32_e32 v85, v85
	s_waitcnt lgkmcnt(12)
	v_mfma_f32_32x32x16_bf16 v[18:33], v[134:137], v[150:153], v[18:33]
	v_exp_f32_e32 v86, v86
	v_exp_f32_e32 v87, v87
	v_exp_f32_e32 v88, v88
	v_exp_f32_e32 v89, v89
	v_add_u32_e32 v110, s28, v203
	ds_read_b128 v[178:181], v110
	ds_read_b128 v[174:177], v110 offset:512
	s_waitcnt lgkmcnt(12)
	v_mfma_f32_32x32x16_bf16 v[34:49], v[10:13], v[114:117], v[34:49]
	v_exp_f32_e32 v90, v90
	v_exp_f32_e32 v91, v91
	v_exp_f32_e32 v92, v92
	v_exp_f32_e32 v93, v93
	ds_read_b128 v[170:173], v110 offset:2048
	ds_read_b128 v[166:169], v110 offset:2560
	s_waitcnt lgkmcnt(12)
	v_mfma_f32_32x32x16_bf16 v[18:33], v[10:13], v[118:121], v[18:33]
	v_exp_f32_e32 v94, v94
	v_exp_f32_e32 v95, v95
	v_exp_f32_e32 v96, v96
	v_exp_f32_e32 v97, v97
	ds_read_b128 v[162:165], v110 offset:4096
	ds_read_b128 v[158:161], v110 offset:4608
	s_waitcnt lgkmcnt(12)
	v_mfma_f32_32x32x16_bf16 v[34:49], v[6:9], v[122:125], v[34:49]
	v_exp_f32_e32 v66, v66
	v_exp_f32_e32 v67, v67
	v_exp_f32_e32 v68, v68
	v_exp_f32_e32 v69, v69
	ds_read_b128 v[154:157], v110 offset:6144
	ds_read_b128 v[150:153], v110 offset:6656
	s_waitcnt lgkmcnt(12)
	v_mfma_f32_32x32x16_bf16 v[18:33], v[6:9], v[98:101], v[18:33]
	v_exp_f32_e32 v70, v70
	v_exp_f32_e32 v71, v71
	v_exp_f32_e32 v72, v72
	v_exp_f32_e32 v73, v73
	s_waitcnt lgkmcnt(10)
	v_mfma_f32_32x32x16_bf16 v[34:49], v[2:5], v[102:105], v[34:49]
	v_exp_f32_e32 v74, v74
	v_exp_f32_e32 v75, v75
	v_exp_f32_e32 v76, v76
	v_exp_f32_e32 v77, v77
	s_waitcnt lgkmcnt(8)
	v_mfma_f32_32x32x16_bf16 v[18:33], v[2:5], v[106:109], v[18:33]
	v_exp_f32_e32 v78, v78
	v_exp_f32_e32 v79, v79
	v_exp_f32_e32 v80, v80
	v_exp_f32_e32 v81, v81
	s_waitcnt vmcnt(2) lgkmcnt(0)
	s_barrier
	s_andn2_b64 vcc, exec, s[8:9]
	s_cbranch_vccnz .LBB0_846
	s_waitcnt lgkmcnt(0)
	v_add_u32_e32 v193, s24, v205
	ds_read_b128 v[98:101], v193 offset:49248
	ds_read_b128 v[102:105], v193 offset:49216
	ds_read_b128 v[106:109], v193 offset:49152
	ds_read_b128 v[110:113], v193 offset:49184
	s_waitcnt lgkmcnt(3)
	v_pk_mul_f32 v[48:49], v[48:49], v[100:101]
	v_pk_mul_f32 v[46:47], v[46:47], v[98:99]
	s_waitcnt lgkmcnt(2)
	v_pk_mul_f32 v[44:45], v[44:45], v[104:105]
	v_pk_mul_f32 v[42:43], v[42:43], v[102:103]
	s_waitcnt lgkmcnt(0)
	v_pk_mul_f32 v[40:41], v[40:41], v[112:113]
	v_pk_mul_f32 v[38:39], v[38:39], v[110:111]
	v_pk_mul_f32 v[36:37], v[36:37], v[108:109]
	v_pk_mul_f32 v[34:35], v[34:35], v[106:107]
	v_pk_mul_f32 v[32:33], v[32:33], v[100:101]
	v_pk_mul_f32 v[30:31], v[30:31], v[98:99]
	v_pk_mul_f32 v[28:29], v[28:29], v[104:105]
	v_pk_mul_f32 v[26:27], v[26:27], v[102:103]
	v_pk_mul_f32 v[24:25], v[24:25], v[112:113]
	v_pk_mul_f32 v[22:23], v[22:23], v[110:111]
	v_pk_mul_f32 v[20:21], v[20:21], v[108:109]
	v_pk_mul_f32 v[18:19], v[18:19], v[106:107]
.LBB0_846:
	s_add_i32 s8, s28, 0x2000
	s_cmpk_lg_i32 s28, 0x4000
	s_cselect_b32 s29, s8, 0
	s_add_i32 s8, s15, 2
	s_add_u32 s36, s36, 0x4000
	s_addc_u32 s37, s37, 0
	s_add_u32 s34, s34, 0x4000
	s_addc_u32 s35, s35, 0
	s_cmp_ge_u32 s8, s25
	s_cbranch_scc1 .Lattn0_steady_exit
	s_mov_b32 s15, s8
	s_mov_b32 s8, s14
	s_mov_b32 s16, s28
	s_mov_b32 s14, s29
	s_branch .LBB0_840
.Lattn0_steady_exit:
	v_lshl_add_u64 v[190:191], s[34:35], 0, v[208:209]
	v_lshl_add_u64 v[188:189], s[36:37], 0, v[210:211]
	s_branch .LBB0_861
